# gla_c: thread to (row, column-group) mapping of the q/k/v stage changed so each load instruction touches 16 rows x 64 B instead of 64 rows x 16 B
# speedup vs baseline: 1.0043x; 1.0043x over previous
.LBB0_816:
	s_cmp_lt_i32 s56, 6
	s_cselect_b64 s[2:3], -1, 0
	s_and_b64 s[66:67], s[2:3], s[0:1]
	s_andn2_b64 vcc, exec, s[66:67]
	s_cbranch_vccnz .LBB0_856
	s_cmpk_lt_i32 s33, 0x800
	v_and_b32_e32 v84, 15, v145
	v_lshrrev_b32_e32 v35, 7, v145
	v_lshrrev_b32_e32 v85, 3, v145
	s_cbranch_scc0 .LBB0_832
	s_add_u32 s68, s54, 0x6800000
	s_waitcnt lgkmcnt(0)
	v_lshrrev_b32_e32 v1, 4, v144
	v_readlane_b32 s45, v244, 6
	s_addc_u32 s69, s55, 0
	v_lshlrev_b32_e32 v0, 3, v1
	s_lshr_b32 s0, s45, 8
	v_readlane_b32 s44, v244, 25
	v_lshrrev_b32_e32 v2, 5, v144
	s_lshl_b32 s1, s44, 5
	v_cmp_eq_u32_e64 s[2:3], s0, v2
	v_lshlrev_b32_e32 v1, 2, v1
	v_and_b32_e32 v2, 8, v0
	v_mov_b32_e32 v31, 0
	s_lshl_b32 s78, s0, 9
	v_lshl_or_b32 v4, s0, 6, v1
	v_lshl_or_b32 v30, s0, 4, v2
	s_and_b32 s0, s1, 0x60
	v_lshlrev_b64 v[2:3], 11, v[30:31]
	v_or_b32_e32 v34, s0, v84
	s_movk_i32 s0, 0x204
	v_lshl_add_u64 v[32:33], s[88:89], 0, v[2:3]
	v_mul_lo_u32 v7, v4, s0
	v_and_b32_e32 v2, 0x7f, v145
	v_and_b32_e32 v4, 1, v35
	v_mul_u32_u24_e32 v6, 0x8100, v4
	v_lshlrev_b32_e32 v2, 2, v2
	v_add3_u32 v8, 0, v6, v2
	v_cmp_eq_u32_e64 s[4:5], 0, v4
	v_cmp_eq_u32_e64 s[6:7], 1, v4
	v_and_b32_e32 v6, 0x300, v145
	v_lshlrev_b32_e32 v4, 7, v4
	v_sub_u32_e32 v4, v4, v6
	v_lshlrev_b32_e32 v4, 2, v4
	s_add_i32 s8, 0, 0x10600
	s_add_i32 s12, 0, 0x10200
	v_lshrrev_b32_e32 v5, 8, v145
	v_add3_u32 v88, s8, v4, v2
	v_lshl_add_u32 v89, v145, 2, s12
	v_lshrrev_b32_e32 v2, 8, v145
	v_lshlrev_b32_e32 v2, 5, v2
	v_and_b32_e32 v135, 3, v145
	v_lshl_add_u32 v2, v135, 3, v2
	v_bfe_u32 v134, v145, 6, 2
	v_lshlrev_b32_e32 v134, 4, v134
	v_bfe_u32 v135, v145, 2, 4
	v_add_u32_e32 v134, v134, v135
	v_mad_u32_u24 v4, v134, s0, 0
	v_or_b32_e32 v6, 7, v2
	s_lshl_b32 s12, s44, 3
	v_mul_u32_u24_e32 v9, 0x4080, v5
	v_cmp_eq_u32_e64 s[8:9], 1, v5
	v_mul_u32_u24_e32 v5, 0x110, v134
	s_add_i32 s42, 0, 0x12800
	v_lshl_add_u32 v90, v2, 2, v4
	v_lshl_add_u32 v91, v6, 2, v4
	v_lshlrev_b32_e32 v4, 1, v2
	s_and_b32 s12, s12, 0x1ffffff0
	s_movk_i32 s0, 0x110
	v_add3_u32 v92, s42, v5, v4
	v_or_b32_e32 v4, s12, v84
	v_mul_lo_u32 v4, v4, s0
	v_and_b32_e32 v5, 48, v144
	s_add_i32 s13, s12, 0x80
	v_add3_u32 v93, s42, v4, v5
	v_or_b32_e32 v4, s13, v84
	v_mul_lo_u32 v4, v4, s0
	v_mul_u32_u24_e32 v12, 0x90, v6
	v_add3_u32 v94, s42, v4, v5
	v_or_b32_e32 v4, s12, v1
	v_and_or_b32 v6, s1, 32, v84
	v_mul_u32_u24_e32 v13, 0x110, v6
	v_or_b32_e32 v15, 1, v4
	v_or_b32_e32 v16, 2, v4
	v_or_b32_e32 v17, 3, v4
	s_bfe_u32 s0, s45, 0x20006
	s_lshl_b32 s1, s44, 4
	s_movk_i32 s43, 0x90
	v_add3_u32 v95, s42, v13, v5
	v_lshl_add_u32 v13, v6, 1, 0
	v_cmp_gt_u32_e64 s[12:13], v6, v4
	v_cmp_lt_u32_e64 s[14:15], v6, v4
	v_cmp_gt_u32_e64 s[16:17], v6, v15
	v_cmp_gt_u32_e64 s[18:19], v6, v16
	v_cmp_lt_u32_e64 s[20:21], v6, v16
	v_cmp_gt_u32_e64 s[22:23], v6, v17
	v_cmp_lt_u32_e64 s[24:25], v6, v17
	v_or_b32_e32 v6, 16, v6
	v_lshl_or_b32 v97, s0, 4, v84
	s_and_b32 s44, s1, 0x3fffffc0
	v_mul_lo_u32 v14, v4, s43
	v_cmp_gt_u32_e64 s[26:27], v6, v4
	v_cmp_lt_u32_e64 s[28:29], v6, v4
	v_mul_u32_u24_e32 v4, 0x110, v97
	v_or_b32_e32 v30, s44, v84
	v_add3_u32 v98, s42, v4, v5
	v_or_b32_e32 v4, 16, v30
	v_mov_b32_e32 v5, v31
	v_cmp_gt_u32_e64 s[30:31], v6, v15
	v_cmp_gt_u32_e64 s[34:35], v6, v16
	v_cmp_lt_u32_e64 s[36:37], v6, v16
	v_cmp_gt_u32_e64 s[38:39], v6, v17
	v_cmp_lt_u32_e64 s[40:41], v6, v17
	v_lshlrev_b64 v[38:39], 8, v[4:5]
	v_or_b32_e32 v4, s44, v1
	v_or3_b32 v6, v1, s1, 48
	v_mbcnt_lo_u32_b32 v1, -1, 0
	v_mbcnt_hi_u32_b32 v1, -1, v1
	v_and_b32_e32 v20, 64, v1
	v_xor_b32_e32 v19, 16, v1
	v_add_u32_e32 v20, 64, v20
	v_cmp_lt_i32_e32 vcc, v19, v20
	v_mul_lo_u32 v18, v30, s43
	v_lshlrev_b64 v[36:37], 8, v[30:31]
	v_or_b32_e32 v30, 32, v30
	s_lshl_b32 s0, s0, 6
	v_cndmask_b32_e32 v19, v1, v19, vcc
	v_lshlrev_b64 v[40:41], 8, v[30:31]
	v_or3_b32 v30, v144, s1, 48
	s_and_b32 s45, s45, 0xffffff00
	s_add_i32 s0, s0, 0
	v_lshlrev_b32_e32 v101, 2, v19
	v_xor_b32_e32 v19, 32, v1
	v_and_b32_e32 v16, 48, v145
	v_mul_lo_u32 v5, v30, s43
	v_lshlrev_b64 v[42:43], 8, v[30:31]
	s_add_i32 s45, s0, s45
	v_lshlrev_b32_e32 v30, 2, v4
	v_cmp_lt_i32_e32 vcc, v19, v20
	v_lshl_add_u32 v3, v34, 2, 0
	s_movk_i32 s10, 0x100
	v_lshl_add_u32 v10, v134, 1, 0
	v_mul_u32_u24_e32 v11, 0x90, v2
	v_mad_u32_u24 v15, v97, s43, 0
	v_add_u32_e32 v17, 0, v16
	s_add_u32 s72, s54, 0x4400000
	v_lshl_add_u64 v[44:45], s[92:93], 0, v[30:31]
	v_lshlrev_b32_e32 v30, 2, v6
	v_cndmask_b32_e32 v1, v1, v19, vcc
	s_mov_b32 s71, 0
	v_or_b32_e32 v86, 0x80, v145
	v_and_b32_e32 v87, 0x37f, v145
	v_cmp_gt_u32_e64 s[10:11], s10, v145
	v_add_u32_e32 v96, 0x1100, v95
	v_cmp_gt_u32_e64 s[42:43], 16, v144
	v_lshl_add_u32 v99, v144, 2, s45
	v_lshl_add_u32 v100, v84, 2, s0
	s_addc_u32 s73, s55, 0
	v_lshl_add_u64 v[46:47], s[92:93], 0, v[30:31]
	v_lshlrev_b32_e32 v102, 2, v1
	s_movk_i32 s79, 0x2600
	s_mov_b32 s80, 0xbfb8aa3b
	s_mov_b32 s81, 0x800000
	s_mov_b32 s82, 0x3f317217
	s_mov_b32 s83, 0x7f800000
	v_lshlrev_b32_e32 v48, 1, v2
	s_mov_b32 s74, 0x3db504f3
	v_add_u32_e32 v103, v10, v11
	v_add_u32_e32 v104, v10, v12
	v_add_u32_e32 v105, v13, v14
	v_add_u32_e32 v106, v15, v16
	v_lshlrev_b32_e32 v30, 1, v0
	v_add_u32_e32 v107, v17, v18
	v_add_u32_e32 v108, v17, v5
	v_mov_b32_e32 v109, 0x358637bd
	s_mov_b64 s[76:77], 0x1140
	v_lshlrev_b32_e32 v50, 1, v4
	v_lshlrev_b32_e32 v52, 1, v6
	v_mov_b32_e32 v110, 0x41b17218
	v_add_u32_e32 v111, v3, v7
	v_add_u32_e32 v112, v8, v9
	s_mov_b32 s84, s33
	global_load_dwordx4 v[212:215], v[44:45], off
	global_load_dwordx4 v[216:219], v[44:45], off offset:64
	global_load_dwordx4 v[220:223], v[44:45], off offset:128
	global_load_dwordx4 v[224:227], v[46:47], off
	s_waitcnt vmcnt(0)
	s_branch .LBB0_820

.LBB0_820:
	s_ashr_i32 s85, s84, 8
	s_and_b32 s45, s84, 63
	s_lshl_b32 s0, s85, 12
	s_lshl_b32 s1, s45, 6
	s_or_b32 s44, s0, s1
	v_or_b32_e32 v6, s44, v84
	v_mov_b64_e32 v[0:1], s[68:69]
	v_mad_i64_i32 v[2:3], s[0:1], v6, s79, v[0:1]
	v_lshl_add_u64 v[2:3], v[2:3], 0, v[30:31]
	v_or_b32_e32 v4, 16, v6
	v_add_co_u32_e32 v2, vcc, 0x1000, v2
	v_mad_i64_i32 v[4:5], s[0:1], v4, s79, v[0:1]
	s_nop 0
	v_addc_co_u32_e32 v3, vcc, 0, v3, vcc
	v_lshl_add_u64 v[4:5], v[4:5], 0, v[30:31]
	v_add_co_u32_e32 v4, vcc, 0x1000, v4
	s_bfe_u32 s86, s84, 0x20006
	s_nop 0
	v_addc_co_u32_e32 v5, vcc, 0, v5, vcc
	global_load_dwordx4 v[12:15], v[2:3], off offset:1344
	global_load_dwordx4 v[8:11], v[4:5], off offset:1344
	v_or_b32_e32 v2, 32, v6
	v_mad_i64_i32 v[2:3], s[0:1], v2, s79, v[0:1]
	v_lshl_add_u64 v[2:3], v[2:3], 0, v[30:31]
	v_or_b32_e32 v4, 48, v6
	v_add_co_u32_e32 v2, vcc, 0x1000, v2
	v_mad_i64_i32 v[0:1], s[0:1], v4, s79, v[0:1]
	s_nop 0
	v_addc_co_u32_e32 v3, vcc, 0, v3, vcc
	v_lshl_add_u64 v[0:1], v[0:1], 0, v[30:31]
	v_add_co_u32_e32 v0, vcc, 0x1000, v0
	s_lshl_b32 s70, s86, 9
	s_nop 0
	v_addc_co_u32_e32 v1, vcc, 0, v1, vcc
	global_load_dwordx4 v[4:7], v[2:3], off offset:1344
	s_nop 0
	global_load_dwordx4 v[0:3], v[0:1], off offset:1344
	v_lshl_add_u64 v[20:21], v[32:33], 0, s[70:71]
	v_lshlrev_b32_e32 v22, 2, v34
	v_mov_b32_e32 v16, 0
	v_mov_b32_e32 v17, 0
	v_mov_b32_e32 v18, 0
	v_mov_b32_e32 v19, 0
	s_lshl_b32 s98, s86, 7
	s_or_b32 s98, s98, s78
	v_or_b32_e32 v208, s98, v34
	v_mov_b32_e32 v209, v31
	v_lshl_add_u64 v[208:209], v[208:209], 2, s[90:91]
	global_load_dword v210, v[208:209], off
	global_load_dword v211, v[208:209], off offset:64
	s_and_saveexec_b64 s[0:1], s[2:3]
	v_mov_b32_e32 v23, v31
	v_lshl_add_u64 v[16:17], v[20:21], 0, v[22:23]
	v_add_co_u32_e32 v18, vcc, 0x1000, v16
	s_nop 1
	v_addc_co_u32_e32 v19, vcc, 0, v17, vcc
	v_add_co_u32_e32 v24, vcc, 0x2000, v16
	s_nop 1
	v_addc_co_u32_e32 v25, vcc, 0, v17, vcc
	v_add_co_u32_e32 v26, vcc, 0x3000, v16
	s_nop 1
	v_addc_co_u32_e32 v27, vcc, 0, v17, vcc
	global_load_dword v200, v[16:17], off offset:64
	global_load_dword v201, v[16:17], off offset:2112
	global_load_dword v202, v[18:19], off offset:64
	global_load_dword v203, v[18:19], off offset:2112
	global_load_dword v204, v[24:25], off offset:64
	global_load_dword v205, v[24:25], off offset:2112
	global_load_dword v206, v[26:27], off offset:64
	global_load_dword v207, v[26:27], off offset:2112
	global_load_dword v23, v[16:17], off
	s_nop 0
	global_load_dword v16, v[16:17], off offset:2048
	s_nop 0
	global_load_dword v17, v[18:19], off
	s_nop 0
	global_load_dword v18, v[18:19], off offset:2048
	s_nop 0
	global_load_dword v19, v[24:25], off
	s_nop 0
	global_load_dword v24, v[24:25], off offset:2048
	s_nop 0
	global_load_dword v25, v[26:27], off
	s_nop 0
	global_load_dword v26, v[26:27], off offset:2048
	s_or_b64 exec, exec, s[0:1]
	v_or_b32_e32 v190, s44, v134
	v_mov_b64_e32 v[174:175], s[68:69]
	v_mad_i64_i32 v[174:175], vcc, v190, s79, v[174:175]
	s_lshl_b32 s100, s86, 8
	s_mov_b32 s101, 0
	v_lshl_add_u64 v[174:175], v[174:175], 0, s[100:101]
	v_mov_b32_e32 v190, v48
	v_mov_b32_e32 v191, v31
	v_lshl_add_u64 v[174:175], v[174:175], 0, v[190:191]
	global_load_dwordx4 v[150:153], v[174:175], off offset:1344
	global_load_dwordx4 v[154:157], v[174:175], off offset:2368
	global_load_dwordx4 v[158:161], v[174:175], off offset:1472
	global_load_dwordx4 v[162:165], v[174:175], off offset:2496
	global_load_dwordx4 v[166:169], v[174:175], off offset:3392
	global_load_dwordx4 v[170:173], v[174:175], off offset:3520
	v_or_b32_e32 v190, s44, v97
	v_mov_b64_e32 v[186:187], s[68:69]
	v_mad_i64_i32 v[186:187], vcc, v190, s79, v[186:187]
	v_lshl_add_u64 v[186:187], v[186:187], 0, s[100:101]
	v_lshl_add_u64 v[186:187], v[186:187], 0, s[76:77]
	v_mov_b32_e32 v190, v50
	v_lshl_add_u64 v[188:189], v[186:187], 0, v[190:191]
	v_mov_b32_e32 v190, v52
	v_lshl_add_u64 v[186:187], v[186:187], 0, v[190:191]
	global_load_dwordx2 v[176:177], v[188:189], off
	global_load_dwordx2 v[178:179], v[188:189], off offset:32
	global_load_dwordx2 v[180:181], v[188:189], off offset:64
	global_load_dwordx2 v[182:183], v[186:187], off
	s_lshl_b32 s98, s85, 3
	s_lshl_b32 s99, s86, 1
	s_or_b32 s98, s99, s98
	s_ashr_i32 s99, s98, 31
	s_lshl_b64 s[98:99], s[98:99], 21
	s_add_u32 s98, s98, s52
	s_addc_u32 s99, s99, s53
	s_lshl_b32 s100, s45, 15
	s_add_u32 s98, s98, s100
	s_addc_u32 s99, s99, 0
	v_readlane_b32 s100, v244, 25
	v_lshrrev_b32_e32 v190, 4, v144
	v_and_b32_e32 v191, 15, v144
	v_lshl_add_u32 v190, s100, 4, v190
	v_lshlrev_b32_e32 v190, 8, v190
	v_lshl_add_u32 v190, v191, 4, v190
	global_load_dwordx4 v[192:195], v190, s[98:99]
	global_load_dwordx4 v[196:199], v190, s[98:99] offset:1024
	global_load_dwordx4 v[232:235], v190, s[98:99] offset:2048
	global_load_dwordx4 v[236:239], v190, s[98:99] offset:3072
	s_waitcnt vmcnt(14)
	s_and_saveexec_b64 s[0:1], s[2:3]
	v_cvt_pk_bf16_f32 v16, v23, v16
	v_cvt_pk_bf16_f32 v17, v17, v18
	v_cvt_pk_bf16_f32 v18, v19, v24
	v_cvt_pk_bf16_f32 v19, v25, v26
